# attention loop edge: K-fragment reads lead the post-barrier segment, DMA issue block in their latency shadow; slot/address setup and exit compare hoisted before the barrier
# baseline (speedup 1.0000x reference)
; #define AT_LOAD(X, t) do { const size_t adv_ = (size_t)(t) * 64; sk##X = *(const u32x4*)(gk + adv_ * 1024); sv##X = *(const u32x4*)(gv + adv_ * 1024); if (rth) sr##X = *(const u32x4*)(gr + adv_ * 32); } while (0)
; #define AT_STORE(X, slot) do { *(LAS u32x4*)(lds + A_K0 + (slot) * AK_BYTES + lk) = sk##X; *(LAS u32x4*)(lds + A_V0 + (slot) * AV_BYTES + lv) = sv##X; if (rth) *(LAS u32x4*)(lds + A_K0 + (slot) * AK_BYTES + lr) = sr##X; } while (0)
; __device__ __forceinline__ void attn_unit(LAS char* lds, const bf16_t* Qp, const bf16_t* KVp, const bf16_t* KRp, int ntiles, bf16_t* Yp, bool dry) {
;     ...
;     const int krow = tid >> 3, kc = tid & 7, rrow = tid >> 2, rc = tid & 3;
;     const bf16_t* gk = KVp + (size_t)krow * 1024 + kc * 8;
;     const bf16_t* gv = gk + 512;
;     const bf16_t* gr = KRp + (size_t)rrow * 32 + rc * 8;
;     const int lk = krow * AK_PITCH + kc * 16, lr = rrow * AK_PITCH + 128 + rc * 16, lv = (kc >> 2) * 4096 + krow * 64 + (kc & 3) * 16;
;     const bool rth = tid < 256;
;     u32x4 skA, svA, srA = {0u, 0u, 0u, 0u}, skB, svB, srB = {0u, 0u, 0u, 0u};
;     ...
;     for (int t = 0; t < ntiles; t += 2) {
;         const int sb0 = (t & 2);
;         const bool more = (t + 2 < ntiles);
;         f32x16 pa0 = {}, pa1 = {}, pb0 = {}, pb1 = {};
;         AT_QK(sb0, pa0, pa1);
;         AT_QK(sb0 + 1, pb0, pb1);
;         if (t == 0) AT_SMPV(sb0, true, pa0, pa1); else AT_SMPV(sb0, false, pa0, pa1);
;         __builtin_amdgcn_sched_barrier(0);
;         if (more) { AT_LOAD(A, t + 2); AT_LOAD(B, t + 3); }
;         AT_SMPV(sb0 + 1, false, pb0, pb1);
;         if (more) { AT_STORE(A, sb0 ^ 2); AT_STORE(B, (sb0 ^ 2) + 1); }
.Latt_iter:
	s_waitcnt vmcnt(0)
	v_xor_b32_e32 v82, 0x80000000, v189
	v_mov_b32_e32 v83, v82
	v_mov_b32_e32 v84, v82
	v_mov_b32_e32 v85, v82
	v_mov_b32_e32 v86, v82
	v_mov_b32_e32 v87, v82
	v_mov_b32_e32 v88, v82
	v_mov_b32_e32 v89, v82
	v_mov_b32_e32 v90, v82
	v_mov_b32_e32 v91, v82
	v_mov_b32_e32 v92, v82
	v_mov_b32_e32 v93, v82
	v_mov_b32_e32 v94, v82
	v_mov_b32_e32 v95, v82
	v_mov_b32_e32 v96, v82
	v_mov_b32_e32 v97, v82
	s_ashr_i32 s14, s8, 6
	s_mul_i32 s2, s14, 0x480000
	s_bfe_u32 s15, s8, 0x30003
	s_lshl_b32 s15, s15, 7
	s_add_i32 s2, s2, s15
	s_add_u32 s2, s2, 0x2f440000
	s_add_u32 s2, s88, s2
	s_addc_u32 s3, s89, 0
	s_mul_i32 s16, s14, 0x24000
	s_add_u32 s16, s16, 0x3cc02000
	s_add_u32 s16, s88, s16
	s_addc_u32 s17, s89, 0
	v_mov_b32_e32 v180, 0x40000
	v_mov_b32_e32 v181, 0x2000
	v_mov_b32_e32 v146, v182
	v_cmp_lt_u32_e32 vcc, 831, v146
	v_cndmask_b32_e64 v147, 0, 1, vcc
	v_mul_u32_u24_e32 v148, 832, v147
	v_sub_u32_e32 v146, v146, v148
	v_mul_u32_u24_e32 v148, 5042, v146
	v_lshrrev_b32_e32 v148, 16, v148
	v_mul_u32_u24_e32 v149, 13, v148
	v_sub_u32_e32 v149, v146, v149
	v_cmp_eq_u32_e32 vcc, 12, v149
	v_cndmask_b32_e64 v149, v149, 0, vcc
	v_lshlrev_b32_e32 v150, 17, v147
	v_lshl_add_u32 v150, v148, 11, v150
	v_lshl_add_u32 v150, v149, 4, v150
	v_lshlrev_b32_e32 v151, 12, v147
	v_lshl_add_u32 v151, v148, 6, v151
	v_lshl_add_u32 v151, v149, 4, v151
	v_add_u32_e32 v151, 0xffffff80, v151
	v_cmp_lt_u32_e64 s[14:15], 7, v149
	v_cndmask_b32_e64 v150, v150, v151, s[14:15]
	v_mov_b32_e32 v152, s2
	v_mov_b32_e32 v153, s3
	v_mov_b32_e32 v178, s16
	v_mov_b32_e32 v179, s17
	v_cndmask_b32_e64 v152, v152, v178, s[14:15]
	v_cndmask_b32_e64 v153, v153, v179, s[14:15]
	v_cndmask_b32_e64 v142, v180, v181, s[14:15]
	v_add_co_u32_e32 v130, vcc, v150, v152
	s_nop 1
	v_addc_co_u32_e32 v131, vcc, 0, v153, vcc
	v_add_u32_e32 v146, 512, v182
	v_cmp_lt_u32_e32 vcc, 831, v146
	v_cndmask_b32_e64 v147, 0, 1, vcc
	v_mul_u32_u24_e32 v148, 832, v147
	v_sub_u32_e32 v146, v146, v148
	v_mul_u32_u24_e32 v148, 5042, v146
	v_lshrrev_b32_e32 v148, 16, v148
	v_mul_u32_u24_e32 v149, 13, v148
	v_sub_u32_e32 v149, v146, v149
	v_cmp_eq_u32_e32 vcc, 12, v149
	v_cndmask_b32_e64 v149, v149, 0, vcc
	v_lshlrev_b32_e32 v150, 17, v147
	v_lshl_add_u32 v150, v148, 11, v150
	v_lshl_add_u32 v150, v149, 4, v150
	v_lshlrev_b32_e32 v151, 12, v147
	v_lshl_add_u32 v151, v148, 6, v151
	v_lshl_add_u32 v151, v149, 4, v151
	v_add_u32_e32 v151, 0xffffff80, v151
	v_cmp_lt_u32_e64 s[14:15], 7, v149
	v_cndmask_b32_e64 v150, v150, v151, s[14:15]
	v_mov_b32_e32 v152, s2
	v_mov_b32_e32 v153, s3
	v_mov_b32_e32 v178, s16
	v_mov_b32_e32 v179, s17
	v_cndmask_b32_e64 v152, v152, v178, s[14:15]
	v_cndmask_b32_e64 v153, v153, v179, s[14:15]
	v_cndmask_b32_e64 v143, v180, v181, s[14:15]
	v_add_co_u32_e32 v132, vcc, v150, v152
	s_nop 1
	v_addc_co_u32_e32 v133, vcc, 0, v153, vcc
	v_add_u32_e32 v146, 1024, v182
	v_cmp_lt_u32_e32 vcc, 831, v146
	v_cndmask_b32_e64 v147, 0, 1, vcc
	v_mul_u32_u24_e32 v148, 832, v147
	v_sub_u32_e32 v146, v146, v148
	v_mul_u32_u24_e32 v148, 5042, v146
	v_lshrrev_b32_e32 v148, 16, v148
	v_mul_u32_u24_e32 v149, 13, v148
	v_sub_u32_e32 v149, v146, v149
	v_cmp_eq_u32_e32 vcc, 12, v149
	v_cndmask_b32_e64 v149, v149, 0, vcc
	v_lshlrev_b32_e32 v150, 17, v147
	v_lshl_add_u32 v150, v148, 11, v150
	v_lshl_add_u32 v150, v149, 4, v150
	v_lshlrev_b32_e32 v151, 12, v147
	v_lshl_add_u32 v151, v148, 6, v151
	v_lshl_add_u32 v151, v149, 4, v151
	v_add_u32_e32 v151, 0xffffff80, v151
	v_cmp_lt_u32_e64 s[14:15], 7, v149
	v_cndmask_b32_e64 v150, v150, v151, s[14:15]
	v_mov_b32_e32 v152, s2
	v_mov_b32_e32 v153, s3
	v_mov_b32_e32 v178, s16
	v_mov_b32_e32 v179, s17
	v_cndmask_b32_e64 v152, v152, v178, s[14:15]
	v_cndmask_b32_e64 v153, v153, v179, s[14:15]
	v_cndmask_b32_e64 v144, v180, v181, s[14:15]
	v_add_co_u32_e32 v134, vcc, v150, v152
	s_nop 1
	v_addc_co_u32_e32 v135, vcc, 0, v153, vcc
	v_add_u32_e32 v146, 1536, v182
	v_cmp_lt_u32_e32 vcc, 831, v146
	v_cndmask_b32_e64 v147, 0, 1, vcc
	v_mul_u32_u24_e32 v148, 832, v147
	v_sub_u32_e32 v146, v146, v148
	v_mul_u32_u24_e32 v148, 5042, v146
	v_lshrrev_b32_e32 v148, 16, v148
	v_mul_u32_u24_e32 v149, 13, v148
	v_sub_u32_e32 v149, v146, v149
	v_cmp_eq_u32_e32 vcc, 12, v149
	v_cndmask_b32_e64 v149, v149, 0, vcc
	v_lshlrev_b32_e32 v150, 17, v147
	v_lshl_add_u32 v150, v148, 11, v150
	v_lshl_add_u32 v150, v149, 4, v150
	v_lshlrev_b32_e32 v151, 12, v147
	v_lshl_add_u32 v151, v148, 6, v151
	v_lshl_add_u32 v151, v149, 4, v151
	v_add_u32_e32 v151, 0xffffff80, v151
	v_cmp_lt_u32_e64 s[14:15], 7, v149
	v_cndmask_b32_e64 v150, v150, v151, s[14:15]
	v_mov_b32_e32 v152, s2
	v_mov_b32_e32 v153, s3
	v_mov_b32_e32 v178, s16
	v_mov_b32_e32 v179, s17
	v_cndmask_b32_e64 v152, v152, v178, s[14:15]
	v_cndmask_b32_e64 v153, v153, v179, s[14:15]
	v_cndmask_b32_e64 v145, v180, v181, s[14:15]
	v_add_co_u32_e32 v136, vcc, v150, v152
	s_nop 1
	v_addc_co_u32_e32 v137, vcc, 0, v153, vcc
	v_bfe_u32 v146, v182, 6, 2
	v_bfe_u32 v147, v182, 2, 4
	v_lshl_add_u32 v146, v146, 4, v147
	v_bfe_u32 v147, v182, 8, 1
	v_and_b32_e32 v148, 3, v182
	v_lshl_add_u32 v147, v147, 2, v148
	v_lshlrev_b32_e32 v146, 11, v146
	v_lshl_add_u32 v146, v147, 4, v146
	v_add_u32_e32 v146, 0x400, v146
	v_mov_b32_e32 v147, s3
	v_add_co_u32_e32 v138, vcc, s2, v146
	s_nop 1
	v_addc_co_u32_e32 v139, vcc, 0, v147, vcc
	v_add_co_u32_e32 v140, vcc, 0x20000, v138
	s_nop 1
	v_addc_co_u32_e32 v141, vcc, 0, v139, vcc
	s_and_b32 s42, s35, 2
	s_mul_i32 s2, s42, 0x3400
	v_add_u32_e32 v0, s2, v209
	v_lshl_add_u32 v185, s42, 13, v208
	v_add_u32_e32 v184, 0x2000, v185
.Latt_loop:
	ds_read_b128 v[66:69], v0 offset:0
	ds_read_b128 v[70:73], v0 offset:6656
	ds_read_b128 v[74:77], v0 offset:32
	ds_read_b128 v[78:81], v0 offset:6688
	ds_read_b128 v[212:215], v0 offset:64
	ds_read_b128 v[240:243], v0 offset:6720
	ds_read_b128 v[244:247], v0 offset:96
	s_cmp_gt_u32 s35, 33
	s_cbranch_scc1 .Latt_noload
	s_xor_b32 s14, s42, 2
	s_mul_i32 s15, s14, 0x3400
	s_lshl_b32 s16, s29, 10
	s_add_i32 s15, s15, s16
	s_mov_b32 m0, s15
	s_add_i32 s15, s15, 0x2000
	global_load_lds_dwordx4 v[130:131], off
	s_mov_b32 m0, s15
	s_add_i32 s15, s15, 0x2000
	global_load_lds_dwordx4 v[132:133], off
	s_mov_b32 m0, s15
	s_add_i32 s15, s15, 0x2000
	global_load_lds_dwordx4 v[134:135], off
	s_cmp_gt_u32 s29, 1
	s_cbranch_scc1 .Latt_dk3
	s_mov_b32 m0, s15
	s_nop 0
	global_load_lds_dwordx4 v[136:137], off

; __device__ __forceinline__ void attn_unit(LAS char* lds, const bf16_t* Qp, const bf16_t* KVp, const bf16_t* KRp, int ntiles, bf16_t* Yp, bool dry) {
;     ...
;         AT_QK(sb0, pa0, pa1);
;         AT_QK(sb0 + 1, pb0, pb1);
.Latt_noload:
	s_waitcnt lgkmcnt(6)
	v_mfma_f32_32x32x16_bf16 v[114:129], v[66:69], v[154:157], v[82:97]
	ds_read_b128 v[248:251], v0 offset:6752
	s_waitcnt lgkmcnt(6)
	v_mfma_f32_32x32x16_bf16 v[98:113], v[70:73], v[154:157], v[82:97]
	ds_read_b128 v[66:69], v0 offset:128
	s_waitcnt lgkmcnt(6)
	v_mfma_f32_32x32x16_bf16 v[114:129], v[74:77], v[158:161], v[114:129]
	ds_read_b128 v[70:73], v0 offset:6784
	s_waitcnt lgkmcnt(6)
	v_mfma_f32_32x32x16_bf16 v[98:113], v[78:81], v[158:161], v[98:113]
	ds_read_b128 v[74:77], v0 offset:160
	s_waitcnt lgkmcnt(6)
	v_mfma_f32_32x32x16_bf16 v[114:129], v[212:215], v[162:165], v[114:129]
	ds_read_b128 v[78:81], v0 offset:6816
	s_waitcnt lgkmcnt(6)
	v_mfma_f32_32x32x16_bf16 v[98:113], v[240:243], v[162:165], v[98:113]
	ds_read_b128 v[212:215], v0 offset:13312
	s_waitcnt lgkmcnt(6)
	v_mfma_f32_32x32x16_bf16 v[114:129], v[244:247], v[166:169], v[114:129]
	ds_read_b128 v[240:243], v0 offset:19968
	s_waitcnt lgkmcnt(6)
	v_mfma_f32_32x32x16_bf16 v[98:113], v[248:251], v[166:169], v[98:113]
	ds_read_b128 v[244:247], v0 offset:13344
	s_waitcnt lgkmcnt(6)
	v_mfma_f32_32x32x16_bf16 v[114:129], v[66:69], v[170:173], v[114:129]
	ds_read_b128 v[248:251], v0 offset:20000
	s_waitcnt lgkmcnt(6)
	v_mfma_f32_32x32x16_bf16 v[98:113], v[70:73], v[170:173], v[98:113]
	ds_read_b128 v[66:69], v0 offset:13376
	s_waitcnt lgkmcnt(6)
	v_mfma_f32_32x32x16_bf16 v[114:129], v[74:77], v[174:177], v[114:129]
	ds_read_b128 v[70:73], v0 offset:20032
	s_waitcnt lgkmcnt(6)
	v_mfma_f32_32x32x16_bf16 v[98:113], v[78:81], v[174:177], v[98:113]
	ds_read_b128 v[74:77], v0 offset:13408
	s_waitcnt lgkmcnt(6)
	v_mfma_f32_32x32x16_bf16 v[2:17], v[212:215], v[154:157], v[82:97]
	ds_read_b128 v[78:81], v0 offset:20064
	s_waitcnt lgkmcnt(6)
	v_mfma_f32_32x32x16_bf16 v[18:33], v[240:243], v[154:157], v[82:97]
	ds_read_b128 v[212:215], v0 offset:13440
	s_waitcnt lgkmcnt(6)
	v_mfma_f32_32x32x16_bf16 v[2:17], v[244:247], v[158:161], v[2:17]
	ds_read_b128 v[240:243], v0 offset:20096
	s_waitcnt lgkmcnt(6)
	v_mfma_f32_32x32x16_bf16 v[18:33], v[248:251], v[158:161], v[18:33]
	ds_read_b128 v[244:247], v0 offset:13472
	s_waitcnt lgkmcnt(6)
	v_mfma_f32_32x32x16_bf16 v[2:17], v[66:69], v[162:165], v[2:17]
	ds_read_b128 v[248:251], v0 offset:20128
	s_waitcnt lgkmcnt(6)
	v_mfma_f32_32x32x16_bf16 v[18:33], v[70:73], v[162:165], v[18:33]
	ds_read_b64_tr_b16 v[216:217], v185 offset:53248
	ds_read_b64_tr_b16 v[218:219], v185 offset:53760
	s_waitcnt lgkmcnt(7)
	v_mfma_f32_32x32x16_bf16 v[2:17], v[74:77], v[166:169], v[2:17]
	ds_read_b64_tr_b16 v[220:221], v185 offset:57344
	ds_read_b64_tr_b16 v[222:223], v185 offset:57856
	s_waitcnt lgkmcnt(8)
	v_mfma_f32_32x32x16_bf16 v[18:33], v[78:81], v[166:169], v[18:33]
	ds_read_b64_tr_b16 v[224:225], v185 offset:54272
	ds_read_b64_tr_b16 v[226:227], v185 offset:54784
	s_waitcnt lgkmcnt(9)
	v_mfma_f32_32x32x16_bf16 v[2:17], v[212:215], v[170:173], v[2:17]
	ds_read_b64_tr_b16 v[228:229], v185 offset:58368
	ds_read_b64_tr_b16 v[230:231], v185 offset:58880
	s_waitcnt lgkmcnt(10)
	v_mfma_f32_32x32x16_bf16 v[18:33], v[240:243], v[170:173], v[18:33]
	ds_read_b64_tr_b16 v[232:233], v185 offset:55296
	ds_read_b64_tr_b16 v[234:235], v185 offset:55808
	s_waitcnt lgkmcnt(11)
	v_mfma_f32_32x32x16_bf16 v[2:17], v[244:247], v[174:177], v[2:17]
	ds_read_b64_tr_b16 v[236:237], v185 offset:59392
	ds_read_b64_tr_b16 v[238:239], v185 offset:59904
	s_waitcnt lgkmcnt(12)
	v_mfma_f32_32x32x16_bf16 v[18:33], v[248:251], v[174:177], v[18:33]
	s_cmp_lg_u32 s35, 34
	s_cbranch_scc1 .Latt_nogate
	s_mul_i32 s14, s28, 0x1c00
	s_mul_hi_u32 s15, s25, 0x1c00
	s_add_i32 s15, s15, s14
	s_mul_i32 s14, s25, 0x1c00
	s_add_u32 s14, s88, s14
	s_addc_u32 s15, s89, s15
	s_lshl_b32 s2, s34, 1
	s_add_u32 s14, s14, s2
	s_addc_u32 s15, s15, 0
	v_lshlrev_b32_e32 v146, 1, v196
	v_mov_b32_e32 v147, 0
	s_mov_b64 s[2:3], 0x1000
	v_lshl_add_u64 v[146:147], s[14:15], 0, v[146:147]
	v_lshrrev_b32_e32 v148, 3, v191
	v_lshl_add_u64 v[146:147], v[146:147], 0, s[2:3]
	v_or_b32_e32 v148, s24, v148
	v_mad_i64_i32 v[150:151], s[16:17], v148, s13, v[146:147]
	v_or_b32_e32 v149, 8, v148
	global_load_dwordx4 v[130:133], v[150:151], off
	v_mad_i64_i32 v[152:153], s[16:17], v149, s13, v[146:147]
	v_or_b32_e32 v149, 16, v148
	global_load_dwordx4 v[134:137], v[152:153], off
	v_mad_i64_i32 v[150:151], s[16:17], v149, s13, v[146:147]
	v_or_b32_e32 v149, 24, v148
	global_load_dwordx4 v[138:141], v[150:151], off
	v_mad_i64_i32 v[152:153], s[16:17], v149, s13, v[146:147]
	s_nop 0
	global_load_dwordx4 v[142:145], v[152:153], off

; #define AT_LOAD(X, t) do { const size_t adv_ = (size_t)(t) * 64; sk##X = *(const u32x4*)(gk + adv_ * 1024); sv##X = *(const u32x4*)(gv + adv_ * 1024); if (rth) sr##X = *(const u32x4*)(gr + adv_ * 32); } while (0)
; #define AT_STORE(X, slot) do { *(LAS u32x4*)(lds + A_K0 + (slot) * AK_BYTES + lk) = sk##X; *(LAS u32x4*)(lds + A_V0 + (slot) * AV_BYTES + lv) = sv##X; if (rth) *(LAS u32x4*)(lds + A_K0 + (slot) * AK_BYTES + lr) = sr##X; } while (0)
; __device__ __forceinline__ void attn_unit(LAS char* lds, const bf16_t* Qp, const bf16_t* KVp, const bf16_t* KRp, int ntiles, bf16_t* Yp, bool dry) {
;     ...
;     for (int t = 0; t < ntiles; t += 2) {
;         const int sb0 = (t & 2);
;         const bool more = (t + 2 < ntiles);
;         f32x16 pa0 = {}, pa1 = {}, pb0 = {}, pb1 = {};
;         AT_QK(sb0, pa0, pa1);
;         AT_QK(sb0 + 1, pb0, pb1);
;         if (t == 0) AT_SMPV(sb0, true, pa0, pa1); else AT_SMPV(sb0, false, pa0, pa1);
;         __builtin_amdgcn_sched_barrier(0);
;         if (more) { AT_LOAD(A, t + 2); AT_LOAD(B, t + 3); }
;         AT_SMPV(sb0 + 1, false, pb0, pb1);
;         if (more) { AT_STORE(A, sb0 ^ 2); AT_STORE(B, (sb0 ^ 2) + 1); }
;         __syncthreads();
;     }
;     ...
;     lsum += __shfl_xor(lsum, 32);
.Latt_nw:
	s_add_i32 s35, s35, 2
	s_and_b32 s42, s35, 2
	s_mul_i32 s2, s42, 0x3400
	v_add_u32_e32 v0, s2, v209
	v_lshl_add_u32 v185, s42, 13, v208
	v_add_u32_e32 v184, 0x2000, v185
	s_cmp_lt_u32 s35, 36
	s_waitcnt lgkmcnt(0)
	s_barrier
	s_cbranch_scc1 .Latt_loop
	v_and_b32_e32 v3, 64, v203
	v_xor_b32_e32 v2, 32, v203
	v_add_u32_e32 v3, 64, v3
	v_cmp_lt_i32_e32 vcc, v2, v3
	s_nop 1
	v_cndmask_b32_e32 v2, v203, v2, vcc
	v_lshlrev_b32_e32 v98, 2, v2
	s_branch .LBB0_858
